# P7 epilogue: 8 SS loads + rstd hoisted to epilogue top, no per-block vmcnt waits
# baseline (speedup 1.0000x reference)
; #define PG8_STAGE(bufoff, gbase, voff) do { _Pragma("unroll") for (int _i = 0; _i < 2; ++_i) \
;         __builtin_amdgcn_global_load_lds((const unsigned*)((const char*)(gbase) + (voff)[_i]), (PG8_LAS unsigned*)(lds + (bufoff) + ldsw + _i * 8192), 16, 0, 0); } while (0)
; #define PG8_LDA(dst, b, h) do { _Pragma("unroll") for (int m = 0; m < 4; ++m) _Pragma("unroll") for (int k = 0; k < 2; ++k) dst[m][k] = *(const PG8_LAS bf16x8*)(lds + PG8_SA(b, h) + aoff + m * 2048 + k * 1024); } while (0)
; #define PG8_LDB(dst, b, h) do { _Pragma("unroll") for (int n = 0; n < 2; ++n) _Pragma("unroll") for (int k = 0; k < 2; ++k) dst[n][k] = *(const PG8_LAS bf16x8*)(lds + PG8_SB(b, h) + boff + n * 2048 + k * 1024); } while (0)
; #define PG8_MMA(ai, bj, At, Bt) do { __builtin_amdgcn_s_setprio(1); _Pragma("unroll") for (int m = 0; m < 4; ++m) _Pragma("unroll") for (int n = 0; n < 2; ++n) _Pragma("unroll") for (int k = 0; k < 2; ++k) \
;         acc[ai][bj][m][n] = __builtin_amdgcn_mfma_f32_16x16x32_bf16(Bt[n][k], At[m][k], acc[ai][bj][m][n], 0, 0, 0); __builtin_amdgcn_s_setprio(0); } while (0)
; #define PG8_WAIT_V(n) asm volatile("s_waitcnt vmcnt(" #n ")" ::: "memory")
; #define PG8_WAIT_L(n) asm volatile("s_waitcnt lgkmcnt(" #n ")" ::: "memory")
; #define PG8_BAR __builtin_amdgcn_s_barrier()
; #define PG8_SCHED __builtin_amdgcn_sched_barrier(0)
; template <class Epi, class Sched, bool ALIGN_EPI = false, bool SP2 = false>
; __device__ __forceinline__ void gemm_phase(PG8_LAS unsigned char* lds, const Gemm g, const Sched& S, const Epi& E, const int tid_arg) {
;     ...
;             PG8_LDB(B0, 0, 0); PG8_LDB(B1, 0, 1); PG8_SCHED; PG8_LDA(At, 0, 0); PG8_STAGE(PG8_SA(1, 1), a1 + hstep, voffA);
;             PG8_WAIT_V(8); PG8_WAIT_L(0); PG8_BAR; PG8_MMA(0, 0, At, B0); PG8_MMA(0, 1, At, B1); PG8_BAR; PG8_SCHED;
;             PG8_LDA(At, 0, 1); PG8_STAGE(PG8_SB(0, 0), b2, voffB); PG8_STAGE(PG8_SB(0, 1), b2 + hstep, voffB); PG8_STAGE(PG8_SA(0, 0), a2, voffA);
;             PG8_WAIT_V(8); PG8_WAIT_L(0); PG8_BAR; PG8_MMA(1, 0, At, B0); PG8_MMA(1, 1, At, B1); PG8_BAR; PG8_SCHED;
.LBB0_1080:
	ds_read_b128 v[148:151], v155
	ds_read_b128 v[160:163], v155 offset:1024
	ds_read_b128 v[164:167], v155 offset:2048
	ds_read_b128 v[168:171], v155 offset:3072
	ds_read_b128 v[172:175], v156
	ds_read_b128 v[176:179], v156 offset:1024
	ds_read_b128 v[182:185], v156 offset:2048
	ds_read_b128 v[186:189], v156 offset:3072
	s_add_u32 s30, s28, 0xfffc0080
	s_addc_u32 s31, s29, -1
	s_cmp_eq_u32 s51, 12
	s_cselect_b32 s35, s21, s31
	s_cselect_b32 s34, s47, s30
	s_cselect_b32 s31, s17, s50
	s_cselect_b32 s30, s48, s49
	v_lshl_add_u64 v[194:195], s[28:29], 0, v[140:141]
	s_add_i32 m0, s27, 0xc000
	ds_read_b128 v[190:193], v157
	ds_read_b128 v[202:205], v157 offset:1024
	ds_read_b128 v[206:209], v157 offset:2048
	ds_read_b128 v[210:213], v157 offset:3072
	ds_read_b128 v[214:217], v157 offset:4096
	ds_read_b128 v[218:221], v157 offset:5120
	ds_read_b128 v[222:225], v157 offset:6144
	ds_read_b128 v[226:229], v157 offset:7168
	global_load_lds_dwordx4 v[194:195], off
	v_lshl_add_u64 v[194:195], s[28:29], 0, v[142:143]
	s_add_i32 m0, s27, 0xe000
	s_nop 0
	global_load_lds_dwordx4 v[194:195], off
	s_waitcnt vmcnt(8)
	s_waitcnt lgkmcnt(0)
	s_barrier
	s_setprio 1
	s_waitcnt lgkmcnt(0)
	v_mfma_f32_16x16x32_bf16 v[126:129], v[148:151], v[190:193], v[126:129]
	v_mfma_f32_16x16x32_bf16 v[122:125], v[164:167], v[190:193], v[122:125]
	v_mfma_f32_16x16x32_bf16 v[110:113], v[148:151], v[206:209], v[110:113]
	v_mfma_f32_16x16x32_bf16 v[106:109], v[164:167], v[206:209], v[106:109]
	v_mfma_f32_16x16x32_bf16 v[94:97], v[148:151], v[214:217], v[94:97]
	v_mfma_f32_16x16x32_bf16 v[90:93], v[164:167], v[214:217], v[90:93]
	v_mfma_f32_16x16x32_bf16 v[78:81], v[148:151], v[222:225], v[78:81]
	v_mfma_f32_16x16x32_bf16 v[74:77], v[164:167], v[222:225], v[74:77]
	v_mfma_f32_16x16x32_bf16 v[126:129], v[160:163], v[202:205], v[126:129]
	v_mfma_f32_16x16x32_bf16 v[122:125], v[168:171], v[202:205], v[122:125]
	v_mfma_f32_16x16x32_bf16 v[110:113], v[160:163], v[210:213], v[110:113]
	v_mfma_f32_16x16x32_bf16 v[106:109], v[168:171], v[210:213], v[106:109]
	v_mfma_f32_16x16x32_bf16 v[94:97], v[160:163], v[218:221], v[94:97]
	v_mfma_f32_16x16x32_bf16 v[90:93], v[168:171], v[218:221], v[90:93]
	v_mfma_f32_16x16x32_bf16 v[78:81], v[160:163], v[226:229], v[78:81]
	v_mfma_f32_16x16x32_bf16 v[74:77], v[168:171], v[226:229], v[74:77]
	s_setprio 0
	s_setprio 1
	v_mfma_f32_16x16x32_bf16 v[118:121], v[172:175], v[190:193], v[118:121]
	v_mfma_f32_16x16x32_bf16 v[114:117], v[182:185], v[190:193], v[114:117]
	v_mfma_f32_16x16x32_bf16 v[102:105], v[172:175], v[206:209], v[102:105]
	v_mfma_f32_16x16x32_bf16 v[98:101], v[182:185], v[206:209], v[98:101]
	v_mfma_f32_16x16x32_bf16 v[86:89], v[172:175], v[214:217], v[86:89]
	v_mfma_f32_16x16x32_bf16 v[82:85], v[182:185], v[214:217], v[82:85]
	v_mfma_f32_16x16x32_bf16 v[70:73], v[172:175], v[222:225], v[70:73]
	v_mfma_f32_16x16x32_bf16 v[66:69], v[182:185], v[222:225], v[66:69]
	v_mfma_f32_16x16x32_bf16 v[118:121], v[176:179], v[202:205], v[118:121]
	v_mfma_f32_16x16x32_bf16 v[114:117], v[186:189], v[202:205], v[114:117]
	v_mfma_f32_16x16x32_bf16 v[102:105], v[176:179], v[210:213], v[102:105]
	v_mfma_f32_16x16x32_bf16 v[98:101], v[186:189], v[210:213], v[98:101]
	v_mfma_f32_16x16x32_bf16 v[86:89], v[176:179], v[218:221], v[86:89]
	v_mfma_f32_16x16x32_bf16 v[82:85], v[186:189], v[218:221], v[82:85]
	v_mfma_f32_16x16x32_bf16 v[70:73], v[176:179], v[226:229], v[70:73]
	v_mfma_f32_16x16x32_bf16 v[66:69], v[186:189], v[226:229], v[66:69]
	s_setprio 0
	s_barrier
	s_add_i32 s52, s42, s33
	v_lshl_add_u64 v[194:195], s[30:31], 0, v[132:133]
	s_mov_b32 m0, s52
	ds_read_b128 v[190:193], v157 offset:16384
	ds_read_b128 v[202:205], v157 offset:17408
	ds_read_b128 v[206:209], v157 offset:18432
	ds_read_b128 v[210:213], v157 offset:19456
	ds_read_b128 v[214:217], v157 offset:20480
	ds_read_b128 v[218:221], v157 offset:21504
	ds_read_b128 v[222:225], v157 offset:22528
	ds_read_b128 v[226:229], v157 offset:23552
	global_load_lds_dwordx4 v[194:195], off
	s_add_i32 m0, s52, 0x2000
	s_add_u32 s52, s30, 0x40000
	v_lshl_add_u64 v[230:231], s[30:31], 0, v[136:137]
	s_addc_u32 s53, s31, 0
	s_add_i32 s54, s43, s33
	global_load_lds_dwordx4 v[230:231], off
	v_lshl_add_u64 v[232:233], s[52:53], 0, v[132:133]
	s_mov_b32 m0, s54
	v_lshl_add_u64 v[234:235], s[34:35], 0, v[134:135]
	global_load_lds_dwordx4 v[232:233], off
	v_lshl_add_u64 v[232:233], s[52:53], 0, v[136:137]
	s_add_i32 m0, s54, 0x2000
	s_nop 0
	global_load_lds_dwordx4 v[232:233], off
	v_lshl_add_u64 v[232:233], s[34:35], 0, v[130:131]
	s_mov_b32 m0, s27
	s_nop 0
	global_load_lds_dwordx4 v[232:233], off
	s_mov_b32 m0, s36
	s_nop 0
	global_load_lds_dwordx4 v[234:235], off
	s_waitcnt vmcnt(8)
	s_waitcnt lgkmcnt(0)
	s_barrier
; #define PG8_STAGE(bufoff, gbase, voff) do { _Pragma("unroll") for (int _i = 0; _i < 2; ++_i) \
;         __builtin_amdgcn_global_load_lds((const unsigned*)((const char*)(gbase) + (voff)[_i]), (PG8_LAS unsigned*)(lds + (bufoff) + ldsw + _i * 8192), 16, 0, 0); } while (0)
; #define PG8_LDA(dst, b, h) do { _Pragma("unroll") for (int m = 0; m < 4; ++m) _Pragma("unroll") for (int k = 0; k < 2; ++k) dst[m][k] = *(const PG8_LAS bf16x8*)(lds + PG8_SA(b, h) + aoff + m * 2048 + k * 1024); } while (0)
; #define PG8_LDB(dst, b, h) do { _Pragma("unroll") for (int n = 0; n < 2; ++n) _Pragma("unroll") for (int k = 0; k < 2; ++k) dst[n][k] = *(const PG8_LAS bf16x8*)(lds + PG8_SB(b, h) + boff + n * 2048 + k * 1024); } while (0)
; #define PG8_MMA(ai, bj, At, Bt) do { __builtin_amdgcn_s_setprio(1); _Pragma("unroll") for (int m = 0; m < 4; ++m) _Pragma("unroll") for (int n = 0; n < 2; ++n) _Pragma("unroll") for (int k = 0; k < 2; ++k) \
;         acc[ai][bj][m][n] = __builtin_amdgcn_mfma_f32_16x16x32_bf16(Bt[n][k], At[m][k], acc[ai][bj][m][n], 0, 0, 0); __builtin_amdgcn_s_setprio(0); } while (0)
; #define PG8_WAIT_V(n) asm volatile("s_waitcnt vmcnt(" #n ")" ::: "memory")
; #define PG8_WAIT_L(n) asm volatile("s_waitcnt lgkmcnt(" #n ")" ::: "memory")
; #define PG8_BAR __builtin_amdgcn_s_barrier()
; #define PG8_SCHED __builtin_amdgcn_sched_barrier(0)
; template <class Epi, class Sched, bool ALIGN_EPI = false, bool SP2 = false>
; __device__ __forceinline__ void gemm_phase(PG8_LAS unsigned char* lds, const Gemm g, const Sched& S, const Epi& E, const int tid_arg) {
;     ...
;             PG8_WAIT_V(8); PG8_WAIT_L(0); PG8_BAR; PG8_MMA(1, 0, At, B0); PG8_MMA(1, 1, At, B1); PG8_BAR; PG8_SCHED;
;             PG8_LDB(B0, 1, 0); PG8_LDB(B1, 1, 1); PG8_SCHED; PG8_LDA(At, 1, 0); PG8_STAGE(PG8_SA(0, 1), a2 + hstep, voffA);
;             PG8_WAIT_V(8); PG8_WAIT_L(0); PG8_BAR; PG8_MMA(0, 0, At, B0); PG8_MMA(0, 1, At, B1); PG8_BAR; PG8_SCHED;
	s_setprio 1
	s_waitcnt lgkmcnt(0)
	v_mfma_f32_16x16x32_bf16 v[62:65], v[148:151], v[190:193], v[62:65]
	v_mfma_f32_16x16x32_bf16 v[58:61], v[164:167], v[190:193], v[58:61]
	v_mfma_f32_16x16x32_bf16 v[46:49], v[148:151], v[206:209], v[46:49]
	v_mfma_f32_16x16x32_bf16 v[42:45], v[164:167], v[206:209], v[42:45]
	v_mfma_f32_16x16x32_bf16 v[30:33], v[148:151], v[214:217], v[30:33]
	v_mfma_f32_16x16x32_bf16 v[26:29], v[164:167], v[214:217], v[26:29]
	v_mfma_f32_16x16x32_bf16 v[14:17], v[148:151], v[222:225], v[14:17]
	v_mfma_f32_16x16x32_bf16 v[10:13], v[164:167], v[222:225], v[10:13]
	v_mfma_f32_16x16x32_bf16 v[62:65], v[160:163], v[202:205], v[62:65]
	v_mfma_f32_16x16x32_bf16 v[58:61], v[168:171], v[202:205], v[58:61]
	v_mfma_f32_16x16x32_bf16 v[46:49], v[160:163], v[210:213], v[46:49]
	v_mfma_f32_16x16x32_bf16 v[42:45], v[168:171], v[210:213], v[42:45]
	v_mfma_f32_16x16x32_bf16 v[30:33], v[160:163], v[218:221], v[30:33]
	v_mfma_f32_16x16x32_bf16 v[26:29], v[168:171], v[218:221], v[26:29]
	v_mfma_f32_16x16x32_bf16 v[14:17], v[160:163], v[226:229], v[14:17]
	v_mfma_f32_16x16x32_bf16 v[10:13], v[168:171], v[226:229], v[10:13]
	s_setprio 0
	s_setprio 1
	v_mfma_f32_16x16x32_bf16 v[54:57], v[172:175], v[190:193], v[54:57]
	v_mfma_f32_16x16x32_bf16 v[50:53], v[182:185], v[190:193], v[50:53]
	v_mfma_f32_16x16x32_bf16 v[38:41], v[172:175], v[206:209], v[38:41]
	v_mfma_f32_16x16x32_bf16 v[34:37], v[182:185], v[206:209], v[34:37]
	v_mfma_f32_16x16x32_bf16 v[22:25], v[172:175], v[214:217], v[22:25]
	v_mfma_f32_16x16x32_bf16 v[18:21], v[182:185], v[214:217], v[18:21]
	v_mfma_f32_16x16x32_bf16 v[6:9], v[172:175], v[222:225], v[6:9]
	v_mfma_f32_16x16x32_bf16 v[2:5], v[182:185], v[222:225], v[2:5]
	v_mfma_f32_16x16x32_bf16 v[54:57], v[176:179], v[202:205], v[54:57]
	v_mfma_f32_16x16x32_bf16 v[50:53], v[186:189], v[202:205], v[50:53]
	v_mfma_f32_16x16x32_bf16 v[38:41], v[176:179], v[210:213], v[38:41]
	v_mfma_f32_16x16x32_bf16 v[34:37], v[186:189], v[210:213], v[34:37]
	v_mfma_f32_16x16x32_bf16 v[22:25], v[176:179], v[218:221], v[22:25]
	v_mfma_f32_16x16x32_bf16 v[18:21], v[186:189], v[218:221], v[18:21]
	v_mfma_f32_16x16x32_bf16 v[6:9], v[176:179], v[226:229], v[6:9]
	v_mfma_f32_16x16x32_bf16 v[2:5], v[186:189], v[226:229], v[2:5]
	s_setprio 0
	s_barrier
	s_add_i32 s52, 0, 0x18000
	v_add_u32_e32 v159, s52, v153
	s_add_i32 s53, 0, 0x1c000
	ds_read_b128 v[148:151], v159
	ds_read_b128 v[160:163], v159 offset:1024
	ds_read_b128 v[164:167], v159 offset:2048
	ds_read_b128 v[168:171], v159 offset:3072
	v_add_u32_e32 v159, s53, v153
	ds_read_b128 v[172:175], v159
	ds_read_b128 v[176:179], v159 offset:1024
	ds_read_b128 v[182:185], v159 offset:2048
	ds_read_b128 v[186:189], v159 offset:3072
	s_add_u32 s34, s34, 0x40000
	s_addc_u32 s35, s35, 0
	s_mov_b32 m0, s37
	v_lshl_add_u64 v[236:237], s[34:35], 0, v[130:131]
	ds_read_b128 v[190:193], v157 offset:32768
	ds_read_b128 v[202:205], v157 offset:33792
	ds_read_b128 v[206:209], v157 offset:34816
	ds_read_b128 v[210:213], v157 offset:35840
	ds_read_b128 v[214:217], v157 offset:36864
	ds_read_b128 v[218:221], v157 offset:37888
	ds_read_b128 v[222:225], v157 offset:38912
	ds_read_b128 v[226:229], v157 offset:39936
	global_load_lds_dwordx4 v[236:237], off
	v_lshl_add_u64 v[236:237], s[34:35], 0, v[134:135]
	s_mov_b32 m0, s38
	s_nop 0
	global_load_lds_dwordx4 v[236:237], off
	s_waitcnt vmcnt(8)
	s_waitcnt lgkmcnt(0)
	s_barrier
	s_setprio 1
	s_waitcnt lgkmcnt(0)
	v_mfma_f32_16x16x32_bf16 v[126:129], v[148:151], v[190:193], v[126:129]
	v_mfma_f32_16x16x32_bf16 v[122:125], v[164:167], v[190:193], v[122:125]
	v_mfma_f32_16x16x32_bf16 v[110:113], v[148:151], v[206:209], v[110:113]
	v_mfma_f32_16x16x32_bf16 v[106:109], v[164:167], v[206:209], v[106:109]
	v_mfma_f32_16x16x32_bf16 v[94:97], v[148:151], v[214:217], v[94:97]
	v_mfma_f32_16x16x32_bf16 v[90:93], v[164:167], v[214:217], v[90:93]
	v_mfma_f32_16x16x32_bf16 v[78:81], v[148:151], v[222:225], v[78:81]
	v_mfma_f32_16x16x32_bf16 v[74:77], v[164:167], v[222:225], v[74:77]
	v_mfma_f32_16x16x32_bf16 v[126:129], v[160:163], v[202:205], v[126:129]
	v_mfma_f32_16x16x32_bf16 v[122:125], v[168:171], v[202:205], v[122:125]
	v_mfma_f32_16x16x32_bf16 v[110:113], v[160:163], v[210:213], v[110:113]
	v_mfma_f32_16x16x32_bf16 v[106:109], v[168:171], v[210:213], v[106:109]
	v_mfma_f32_16x16x32_bf16 v[94:97], v[160:163], v[218:221], v[94:97]
	v_mfma_f32_16x16x32_bf16 v[90:93], v[168:171], v[218:221], v[90:93]
	v_mfma_f32_16x16x32_bf16 v[78:81], v[160:163], v[226:229], v[78:81]
	v_mfma_f32_16x16x32_bf16 v[74:77], v[168:171], v[226:229], v[74:77]
	s_setprio 0
	s_setprio 1
	v_mfma_f32_16x16x32_bf16 v[118:121], v[172:175], v[190:193], v[118:121]
	v_mfma_f32_16x16x32_bf16 v[114:117], v[182:185], v[190:193], v[114:117]
	v_mfma_f32_16x16x32_bf16 v[102:105], v[172:175], v[206:209], v[102:105]
	v_mfma_f32_16x16x32_bf16 v[98:101], v[182:185], v[206:209], v[98:101]
	v_mfma_f32_16x16x32_bf16 v[86:89], v[172:175], v[214:217], v[86:89]
	v_mfma_f32_16x16x32_bf16 v[82:85], v[182:185], v[214:217], v[82:85]
	v_mfma_f32_16x16x32_bf16 v[70:73], v[172:175], v[222:225], v[70:73]
	v_mfma_f32_16x16x32_bf16 v[66:69], v[182:185], v[222:225], v[66:69]
	v_mfma_f32_16x16x32_bf16 v[118:121], v[176:179], v[202:205], v[118:121]
	v_mfma_f32_16x16x32_bf16 v[114:117], v[186:189], v[202:205], v[114:117]
	v_mfma_f32_16x16x32_bf16 v[102:105], v[176:179], v[210:213], v[102:105]
	v_mfma_f32_16x16x32_bf16 v[98:101], v[186:189], v[210:213], v[98:101]
	v_mfma_f32_16x16x32_bf16 v[86:89], v[176:179], v[218:221], v[86:89]
	v_mfma_f32_16x16x32_bf16 v[82:85], v[186:189], v[218:221], v[82:85]
	v_mfma_f32_16x16x32_bf16 v[70:73], v[176:179], v[226:229], v[70:73]
	v_mfma_f32_16x16x32_bf16 v[66:69], v[186:189], v[226:229], v[66:69]
	s_setprio 0
	s_barrier
; #define PG8_STAGE(bufoff, gbase, voff) do { _Pragma("unroll") for (int _i = 0; _i < 2; ++_i) \
;         __builtin_amdgcn_global_load_lds((const unsigned*)((const char*)(gbase) + (voff)[_i]), (PG8_LAS unsigned*)(lds + (bufoff) + ldsw + _i * 8192), 16, 0, 0); } while (0)
; #define PG8_LDA(dst, b, h) do { _Pragma("unroll") for (int m = 0; m < 4; ++m) _Pragma("unroll") for (int k = 0; k < 2; ++k) dst[m][k] = *(const PG8_LAS bf16x8*)(lds + PG8_SA(b, h) + aoff + m * 2048 + k * 1024); } while (0)
; #define PG8_MMA(ai, bj, At, Bt) do { __builtin_amdgcn_s_setprio(1); _Pragma("unroll") for (int m = 0; m < 4; ++m) _Pragma("unroll") for (int n = 0; n < 2; ++n) _Pragma("unroll") for (int k = 0; k < 2; ++k) \
;         acc[ai][bj][m][n] = __builtin_amdgcn_mfma_f32_16x16x32_bf16(Bt[n][k], At[m][k], acc[ai][bj][m][n], 0, 0, 0); __builtin_amdgcn_s_setprio(0); } while (0)
; #define PG8_WAIT_V(n) asm volatile("s_waitcnt vmcnt(" #n ")" ::: "memory")
; #define PG8_WAIT_L(n) asm volatile("s_waitcnt lgkmcnt(" #n ")" ::: "memory")
; #define PG8_BAR __builtin_amdgcn_s_barrier()
; #define PG8_SCHED __builtin_amdgcn_sched_barrier(0)
;     __device__ __forceinline__ void operator()(const f32x4 (&acc)[2][2][4][2], const Unit& u, int wr, int wc, int fr, int fq) const {
;     ...
;                 int row = row0 + ai * HALF + m * 16; asm volatile("" : "+v"(row));
;                 const float rs = SS ? rstd_from_ss(SS + (size_t)row * 16, fq) : 1.0f;
; template <class Epi, class Sched, bool ALIGN_EPI = false, bool SP2 = false>
; __device__ __forceinline__ void gemm_phase(PG8_LAS unsigned char* lds, const Gemm g, const Sched& S, const Epi& E, const int tid_arg) {
;     ...
;             PG8_LDA(At, 1, 1); PG8_STAGE(PG8_SB(1, 0), b3, voffB); PG8_STAGE(PG8_SB(1, 1), b3 + hstep, voffB); PG8_STAGE(PG8_SA(1, 0), a3, voffA);
;             PG8_WAIT_V(8); PG8_WAIT_L(0); PG8_BAR; PG8_MMA(1, 0, At, B0); PG8_MMA(1, 1, At, B1); PG8_BAR; PG8_SCHED;
	s_add_i32 s34, s52, s33
	v_lshl_add_u64 v[194:195], v[194:195], 0, s[12:13]
	s_mov_b32 m0, s34
	ds_read_b128 v[190:193], v157 offset:49152
	ds_read_b128 v[202:205], v157 offset:50176
	ds_read_b128 v[206:209], v157 offset:51200
	ds_read_b128 v[210:213], v157 offset:52224
	ds_read_b128 v[214:217], v157 offset:53248
	ds_read_b128 v[218:221], v157 offset:54272
	ds_read_b128 v[222:225], v157 offset:55296
	ds_read_b128 v[226:229], v157 offset:56320
	global_load_lds_dwordx4 v[194:195], off
	s_add_i32 m0, s34, 0x2000
	s_add_u32 s30, s30, 0x40080
	v_lshl_add_u64 v[194:195], v[230:231], 0, s[12:13]
	s_addc_u32 s31, s31, 0
	s_add_i32 s34, s53, s33
	global_load_lds_dwordx4 v[194:195], off
	v_lshl_add_u64 v[194:195], s[30:31], 0, v[132:133]
	s_mov_b32 m0, s34
	s_nop 0
	global_load_lds_dwordx4 v[194:195], off
	v_lshl_add_u64 v[194:195], s[30:31], 0, v[136:137]
	s_add_i32 m0, s34, 0x2000
	s_nop 0
	global_load_lds_dwordx4 v[194:195], off
	v_lshl_add_u64 v[194:195], v[232:233], 0, s[12:13]
	s_mov_b32 m0, s40
	s_nop 0
	global_load_lds_dwordx4 v[194:195], off
	v_lshl_add_u64 v[194:195], v[234:235], 0, s[12:13]
	s_mov_b32 m0, s41
	s_nop 0
	global_load_lds_dwordx4 v[194:195], off
	s_waitcnt vmcnt(8)
	s_waitcnt lgkmcnt(0)
	s_barrier
	s_setprio 1
	s_waitcnt lgkmcnt(0)
	v_mfma_f32_16x16x32_bf16 v[62:65], v[148:151], v[190:193], v[62:65]
	v_mfma_f32_16x16x32_bf16 v[58:61], v[164:167], v[190:193], v[58:61]
	v_mfma_f32_16x16x32_bf16 v[46:49], v[148:151], v[206:209], v[46:49]
	v_mfma_f32_16x16x32_bf16 v[42:45], v[164:167], v[206:209], v[42:45]
	v_mfma_f32_16x16x32_bf16 v[30:33], v[148:151], v[214:217], v[30:33]
	v_mfma_f32_16x16x32_bf16 v[26:29], v[164:167], v[214:217], v[26:29]
	v_mfma_f32_16x16x32_bf16 v[14:17], v[148:151], v[222:225], v[14:17]
	v_mfma_f32_16x16x32_bf16 v[10:13], v[164:167], v[222:225], v[10:13]
	v_mfma_f32_16x16x32_bf16 v[62:65], v[160:163], v[202:205], v[62:65]
	v_mfma_f32_16x16x32_bf16 v[58:61], v[168:171], v[202:205], v[58:61]
	v_mfma_f32_16x16x32_bf16 v[46:49], v[160:163], v[210:213], v[46:49]
	v_mfma_f32_16x16x32_bf16 v[42:45], v[168:171], v[210:213], v[42:45]
	v_mfma_f32_16x16x32_bf16 v[30:33], v[160:163], v[218:221], v[30:33]
	v_mfma_f32_16x16x32_bf16 v[26:29], v[168:171], v[218:221], v[26:29]
	v_mfma_f32_16x16x32_bf16 v[14:17], v[160:163], v[226:229], v[14:17]
	v_mfma_f32_16x16x32_bf16 v[10:13], v[168:171], v[226:229], v[10:13]
	s_setprio 0
	s_setprio 1
	v_mfma_f32_16x16x32_bf16 v[54:57], v[172:175], v[190:193], v[54:57]
	v_mfma_f32_16x16x32_bf16 v[50:53], v[182:185], v[190:193], v[50:53]
	v_mfma_f32_16x16x32_bf16 v[38:41], v[172:175], v[206:209], v[38:41]
	v_mfma_f32_16x16x32_bf16 v[34:37], v[182:185], v[206:209], v[34:37]
	v_mfma_f32_16x16x32_bf16 v[22:25], v[172:175], v[214:217], v[22:25]
	v_mfma_f32_16x16x32_bf16 v[18:21], v[182:185], v[214:217], v[18:21]
	v_mfma_f32_16x16x32_bf16 v[6:9], v[172:175], v[222:225], v[6:9]
	v_mfma_f32_16x16x32_bf16 v[2:5], v[182:185], v[222:225], v[2:5]
	v_mfma_f32_16x16x32_bf16 v[54:57], v[176:179], v[202:205], v[54:57]
	v_mfma_f32_16x16x32_bf16 v[50:53], v[186:189], v[202:205], v[50:53]
	v_mfma_f32_16x16x32_bf16 v[38:41], v[176:179], v[210:213], v[38:41]
	v_mfma_f32_16x16x32_bf16 v[34:37], v[186:189], v[210:213], v[34:37]
	v_mfma_f32_16x16x32_bf16 v[22:25], v[176:179], v[218:221], v[22:25]
	v_mfma_f32_16x16x32_bf16 v[18:21], v[186:189], v[218:221], v[18:21]
	v_mfma_f32_16x16x32_bf16 v[6:9], v[176:179], v[226:229], v[6:9]
	v_mfma_f32_16x16x32_bf16 v[2:5], v[186:189], v[226:229], v[2:5]
	s_setprio 0
	s_barrier
	s_add_i32 s51, s51, 2
	s_add_u32 s28, s28, 0x100
	s_addc_u32 s29, s29, 0
	s_add_u32 s49, s49, 0x100
	s_addc_u32 s50, s50, 0
	s_cmp_gt_u32 s51, 13
	s_cbranch_scc0 .LBB0_1080
	v_lshl_add_u32 v159, s26, 8, v152
	v_mov_b32_e32 v231, 0
	v_mov_b32_e32 v230, v159
	v_add_u32_e32 v232, 0x80, v159
	v_mov_b32_e32 v233, 0
	v_lshlrev_b64 v[230:231], 6, v[230:231]
	v_lshlrev_b64 v[232:233], 6, v[232:233]
	v_lshl_add_u64 v[230:231], v[138:139], 0, v[230:231]
	v_lshl_add_u64 v[232:233], v[138:139], 0, v[232:233]
	global_load_dwordx4 v[190:193], v[230:231], off
	global_load_dwordx4 v[202:205], v[230:231], off offset:1024
	global_load_dwordx4 v[206:209], v[230:231], off offset:2048
	global_load_dwordx4 v[210:213], v[230:231], off offset:3072
	global_load_dwordx4 v[214:217], v[232:233], off
	global_load_dwordx4 v[218:221], v[232:233], off offset:1024
	global_load_dwordx4 v[222:225], v[232:233], off offset:2048
	global_load_dwordx4 v[226:229], v[232:233], off offset:3072
	s_and_b64 vcc, exec, s[14:15]
	s_cbranch_vccz .LBB0_1083
	s_barrier
; __device__ __forceinline__ unsigned cvt_pk_bf16(float lo, float hi) { f32x2_cv v = {lo, hi}; bf16x2_cv b = __builtin_convertvector(v, bf16x2_cv); return __builtin_bit_cast(unsigned, b); }
; __device__ __forceinline__ float fast_sigmoid(float x) { return __builtin_amdgcn_rcpf(1.0f + __expf(-x)); }
; __device__ __forceinline__ float rstd_from_ss(const float* ssrow, int fq) {
;     const f32x4 a = ((const f32x4*)ssrow)[fq];
;     float s = (a[0] + a[1]) + (a[2] + a[3]);
;     s += __shfl_xor(s, 16); s += __shfl_xor(s, 32);
;     return rsqrtf(s * (1.0f / 1024.0f) + 1e-6f);
; }
;     __device__ __forceinline__ void operator()(const f32x4 (&acc)[2][2][4][2], const Unit& u, int wr, int wc, int fr, int fq) const {
;     ...
;                 int row = row0 + ai * HALF + m * 16; asm volatile("" : "+v"(row));
;                 const float rs = SS ? rstd_from_ss(SS + (size_t)row * 16, fq) : 1.0f;
;                 float o[8];
; #pragma unroll
;                 for (int n = 0; n < 2; ++n)
; #pragma unroll
;                     for (int i = 0; i < 4; ++i) { const float g = acc[ai][0][m][n][i] * rs, up = acc[ai][1][m][n][i] * rs; o[4 * n + i] = g * fast_sigmoid(g) * up; }
;                 u32x4 w; w.x = cvt_pk_bf16(o[0], o[1]); w.y = cvt_pk_bf16(o[2], o[3]); w.z = cvt_pk_bf16(o[4], o[5]); w.w = cvt_pk_bf16(o[6], o[7]);
;                 *(u32x4*)(O + (size_t)row * 2816 + col0) = w;
.LBB0_1083:
	s_waitcnt vmcnt(0)
	v_add_f32_e32 v190, v191, v190
	v_add_f32_e32 v191, v192, v193
	v_add_f32_e32 v202, v203, v202
	v_add_f32_e32 v203, v204, v205
	v_add_f32_e32 v206, v207, v206
	v_add_f32_e32 v207, v208, v209
	v_add_f32_e32 v210, v211, v210
	v_add_f32_e32 v211, v212, v213
	v_add_f32_e32 v214, v215, v214
	v_add_f32_e32 v215, v216, v217
	v_add_f32_e32 v218, v219, v218
	v_add_f32_e32 v219, v220, v221
	v_add_f32_e32 v222, v223, v222
	v_add_f32_e32 v223, v224, v225
	v_add_f32_e32 v226, v227, v226
	v_add_f32_e32 v227, v228, v229
	v_add_f32_e32 v190, v190, v191
	v_add_f32_e32 v202, v202, v203
	v_add_f32_e32 v206, v206, v207
	v_add_f32_e32 v210, v210, v211
	v_add_f32_e32 v214, v214, v215
	v_add_f32_e32 v218, v218, v219
	v_add_f32_e32 v222, v222, v223
	v_add_f32_e32 v226, v226, v227
	ds_bpermute_b32 v191, v199, v190
	ds_bpermute_b32 v203, v199, v202
	ds_bpermute_b32 v207, v199, v206
	ds_bpermute_b32 v211, v199, v210
	ds_bpermute_b32 v215, v199, v214
	ds_bpermute_b32 v219, v199, v218
	ds_bpermute_b32 v223, v199, v222
	ds_bpermute_b32 v227, v199, v226
	s_waitcnt lgkmcnt(0)
	v_add_f32_e32 v190, v190, v191
	v_add_f32_e32 v202, v202, v203
	v_add_f32_e32 v206, v206, v207
	v_add_f32_e32 v210, v210, v211
	v_add_f32_e32 v214, v214, v215
	v_add_f32_e32 v218, v218, v219
	v_add_f32_e32 v222, v222, v223
	v_add_f32_e32 v226, v226, v227
	ds_bpermute_b32 v191, v200, v190
	ds_bpermute_b32 v203, v200, v202
	ds_bpermute_b32 v207, v200, v206
	ds_bpermute_b32 v211, v200, v210
	ds_bpermute_b32 v215, v200, v214
	ds_bpermute_b32 v219, v200, v218
	ds_bpermute_b32 v223, v200, v222
	ds_bpermute_b32 v227, v200, v226
	s_waitcnt lgkmcnt(0)
	v_add_f32_e32 v190, v190, v191
	v_add_f32_e32 v202, v202, v203
	v_add_f32_e32 v206, v206, v207
	v_add_f32_e32 v210, v210, v211
	v_add_f32_e32 v214, v214, v215
	v_add_f32_e32 v218, v218, v219
	v_add_f32_e32 v222, v222, v223
	v_add_f32_e32 v226, v226, v227
	v_fmamk_f32 v190, v190, 0x3a800000, v158
	v_fmamk_f32 v202, v202, 0x3a800000, v158
	v_fmamk_f32 v206, v206, 0x3a800000, v158
	v_fmamk_f32 v210, v210, 0x3a800000, v158
	v_fmamk_f32 v214, v214, 0x3a800000, v158
	v_fmamk_f32 v218, v218, 0x3a800000, v158
	v_fmamk_f32 v222, v222, 0x3a800000, v158
	v_fmamk_f32 v226, v226, 0x3a800000, v158
	v_cmp_gt_f32_e32 vcc, s44, v190
	v_mul_f32_e32 v191, 0x4b800000, v190
	s_nop 0
	v_cndmask_b32_e32 v190, v190, v191, vcc
	v_rsq_f32_e32 v190, v190
	s_nop 0
	v_mul_f32_e32 v191, 0x45800000, v190
	v_cndmask_b32_e32 v190, v190, v191, vcc
	v_cmp_gt_f32_e32 vcc, s44, v202
	v_mul_f32_e32 v203, 0x4b800000, v202
	s_nop 0
	v_cndmask_b32_e32 v202, v202, v203, vcc
	v_rsq_f32_e32 v202, v202
	s_nop 0
	v_mul_f32_e32 v203, 0x45800000, v202
	v_cndmask_b32_e32 v202, v202, v203, vcc
	v_cmp_gt_f32_e32 vcc, s44, v206
	v_mul_f32_e32 v207, 0x4b800000, v206
	s_nop 0
	v_cndmask_b32_e32 v206, v206, v207, vcc
	v_rsq_f32_e32 v206, v206
	s_nop 0
	v_mul_f32_e32 v207, 0x45800000, v206
	v_cndmask_b32_e32 v206, v206, v207, vcc
	v_cmp_gt_f32_e32 vcc, s44, v210
	v_mul_f32_e32 v211, 0x4b800000, v210
	s_nop 0
	v_cndmask_b32_e32 v210, v210, v211, vcc
	v_rsq_f32_e32 v210, v210
	s_nop 0
	v_mul_f32_e32 v211, 0x45800000, v210
	v_cndmask_b32_e32 v210, v210, v211, vcc
	v_cmp_gt_f32_e32 vcc, s44, v214
	v_mul_f32_e32 v215, 0x4b800000, v214
	s_nop 0
	v_cndmask_b32_e32 v214, v214, v215, vcc
	v_rsq_f32_e32 v214, v214
	s_nop 0
	v_mul_f32_e32 v215, 0x45800000, v214
	v_cndmask_b32_e32 v214, v214, v215, vcc
	v_cmp_gt_f32_e32 vcc, s44, v218
	v_mul_f32_e32 v219, 0x4b800000, v218
	s_nop 0
	v_cndmask_b32_e32 v218, v218, v219, vcc
	v_rsq_f32_e32 v218, v218
	s_nop 0
	v_mul_f32_e32 v219, 0x45800000, v218
	v_cndmask_b32_e32 v218, v218, v219, vcc
	v_cmp_gt_f32_e32 vcc, s44, v222
	v_mul_f32_e32 v223, 0x4b800000, v222
	s_nop 0
	v_cndmask_b32_e32 v222, v222, v223, vcc
	v_rsq_f32_e32 v222, v222
	s_nop 0
	v_mul_f32_e32 v223, 0x45800000, v222
	v_cndmask_b32_e32 v222, v222, v223, vcc
	v_cmp_gt_f32_e32 vcc, s44, v226
	v_mul_f32_e32 v227, 0x4b800000, v226
	s_nop 0
	v_cndmask_b32_e32 v226, v226, v227, vcc
	v_rsq_f32_e32 v226, v226
	s_nop 0
	v_mul_f32_e32 v227, 0x45800000, v226
	v_cndmask_b32_e32 v226, v226, v227, vcc
	v_mov_b32_e32 v160, v159
	v_lshl_or_b32 v150, s46, 7, v154
	v_ashrrev_i32_e32 v151, 31, v150
	v_lshlrev_b64 v[150:151], 1, v[150:151]
	v_or_b32_e32 v162, 16, v159
	v_mov_b64_e32 v[148:149], s[6:7]
	v_mad_i64_i32 v[160:161], s[28:29], v160, s45, v[148:149]
	v_lshl_add_u64 v[160:161], v[160:161], 0, v[150:151]
	v_pk_mul_f32 v[126:127], v[126:127], v[190:191] op_sel_hi:[1,0]
	v_pk_mul_f32 v[128:129], v[128:129], v[190:191] op_sel_hi:[1,0]
	v_pk_mul_f32 v[122:123], v[122:123], v[190:191] op_sel_hi:[1,0]
	v_pk_mul_f32 v[124:125], v[124:125], v[190:191] op_sel_hi:[1,0]
	v_pk_mul_f32 v[118:119], v[118:119], v[190:191] op_sel_hi:[1,0]
	v_pk_mul_f32 v[120:121], v[120:121], v[190:191] op_sel_hi:[1,0]
	v_pk_mul_f32 v[114:115], v[114:115], v[190:191] op_sel_hi:[1,0]
	v_pk_mul_f32 v[116:117], v[116:117], v[190:191] op_sel_hi:[1,0]
	v_mul_f32_e32 v163, 0xbfb8aa3b, v126
	v_mul_f32_e32 v164, 0xbfb8aa3b, v127
	v_mul_f32_e32 v165, 0xbfb8aa3b, v128
	v_mul_f32_e32 v166, 0xbfb8aa3b, v129
	v_mul_f32_e32 v167, 0xbfb8aa3b, v122
	v_mul_f32_e32 v168, 0xbfb8aa3b, v123
	v_mul_f32_e32 v169, 0xbfb8aa3b, v124
	v_mul_f32_e32 v170, 0xbfb8aa3b, v125
	v_exp_f32_e32 v163, v163
	v_exp_f32_e32 v164, v164
	v_exp_f32_e32 v165, v165
	v_exp_f32_e32 v166, v166
	v_exp_f32_e32 v167, v167
	v_exp_f32_e32 v168, v168
	v_exp_f32_e32 v169, v169
	v_exp_f32_e32 v170, v170
	v_add_f32_e32 v163, 1.0, v163
	v_add_f32_e32 v171, 1.0, v164
	v_add_f32_e32 v172, 1.0, v165
	v_add_f32_e32 v173, 1.0, v166
	v_add_f32_e32 v174, 1.0, v167
	v_add_f32_e32 v175, 1.0, v168
; __device__ __forceinline__ unsigned cvt_pk_bf16(float lo, float hi) { f32x2_cv v = {lo, hi}; bf16x2_cv b = __builtin_convertvector(v, bf16x2_cv); return __builtin_bit_cast(unsigned, b); }
; __device__ __forceinline__ float fast_sigmoid(float x) { return __builtin_amdgcn_rcpf(1.0f + __expf(-x)); }
;     __device__ __forceinline__ void operator()(const f32x4 (&acc)[2][2][4][2], const Unit& u, int wr, int wc, int fr, int fq) const {
;     ...
;                 int row = row0 + ai * HALF + m * 16; asm volatile("" : "+v"(row));
;                 const float rs = SS ? rstd_from_ss(SS + (size_t)row * 16, fq) : 1.0f;
;                 float o[8];
; #pragma unroll
;                 for (int n = 0; n < 2; ++n)
; #pragma unroll
;                     for (int i = 0; i < 4; ++i) { const float g = acc[ai][0][m][n][i] * rs, up = acc[ai][1][m][n][i] * rs; o[4 * n + i] = g * fast_sigmoid(g) * up; }
;                 u32x4 w; w.x = cvt_pk_bf16(o[0], o[1]); w.y = cvt_pk_bf16(o[2], o[3]); w.z = cvt_pk_bf16(o[4], o[5]); w.w = cvt_pk_bf16(o[6], o[7]);
;                 *(u32x4*)(O + (size_t)row * 2816 + col0) = w;
	v_add_f32_e32 v176, 1.0, v169
	v_add_f32_e32 v177, 1.0, v170
	v_rcp_f32_e32 v164, v163
	v_rcp_f32_e32 v165, v171
	v_rcp_f32_e32 v166, v172
	v_rcp_f32_e32 v167, v173
	v_rcp_f32_e32 v168, v174
	v_rcp_f32_e32 v169, v175
	v_rcp_f32_e32 v170, v176
	v_rcp_f32_e32 v171, v177
	v_pk_mul_f32 v[126:127], v[126:127], v[164:165]
	v_pk_mul_f32 v[128:129], v[128:129], v[166:167]
	v_pk_mul_f32 v[122:123], v[122:123], v[168:169]
	v_pk_mul_f32 v[124:125], v[124:125], v[170:171]
	v_pk_mul_f32 v[118:119], v[118:119], v[126:127]
	v_pk_mul_f32 v[120:121], v[120:121], v[128:129]
	v_pk_mul_f32 v[122:123], v[114:115], v[122:123]
	v_pk_mul_f32 v[124:125], v[116:117], v[124:125]
	v_cvt_pk_bf16_f32 v114, v118, v119
	v_cvt_pk_bf16_f32 v115, v120, v121
	v_cvt_pk_bf16_f32 v116, v122, v123
	v_cvt_pk_bf16_f32 v117, v124, v125
	global_store_dwordx4 v[160:161], v[114:117], off
	s_nop 1
	v_or_b32_e32 v114, 32, v159
	v_mad_i64_i32 v[116:117], s[28:29], v162, s45, v[148:149]
	v_lshl_add_u64 v[116:117], v[116:117], 0, v[150:151]
	v_pk_mul_f32 v[110:111], v[110:111], v[202:203] op_sel_hi:[1,0]
	v_pk_mul_f32 v[112:113], v[112:113], v[202:203] op_sel_hi:[1,0]
	v_pk_mul_f32 v[106:107], v[106:107], v[202:203] op_sel_hi:[1,0]
	v_pk_mul_f32 v[108:109], v[108:109], v[202:203] op_sel_hi:[1,0]
	v_pk_mul_f32 v[102:103], v[102:103], v[202:203] op_sel_hi:[1,0]
	v_pk_mul_f32 v[104:105], v[104:105], v[202:203] op_sel_hi:[1,0]
	v_pk_mul_f32 v[98:99], v[98:99], v[202:203] op_sel_hi:[1,0]
	v_pk_mul_f32 v[100:101], v[100:101], v[202:203] op_sel_hi:[1,0]
	v_mul_f32_e32 v115, 0xbfb8aa3b, v110
	v_mul_f32_e32 v118, 0xbfb8aa3b, v111
	v_mul_f32_e32 v119, 0xbfb8aa3b, v112
	v_mul_f32_e32 v120, 0xbfb8aa3b, v113
	v_mul_f32_e32 v121, 0xbfb8aa3b, v106
	v_mul_f32_e32 v122, 0xbfb8aa3b, v107
	v_mul_f32_e32 v123, 0xbfb8aa3b, v108
	v_mul_f32_e32 v124, 0xbfb8aa3b, v109
	v_exp_f32_e32 v115, v115
	v_exp_f32_e32 v118, v118
	v_exp_f32_e32 v119, v119
	v_exp_f32_e32 v120, v120
	v_exp_f32_e32 v121, v121
	v_exp_f32_e32 v122, v122
	v_exp_f32_e32 v123, v123
	v_exp_f32_e32 v124, v124
	v_add_f32_e32 v115, 1.0, v115
	v_add_f32_e32 v125, 1.0, v118
	v_add_f32_e32 v126, 1.0, v119
	v_add_f32_e32 v127, 1.0, v120
	v_add_f32_e32 v128, 1.0, v121
	v_add_f32_e32 v129, 1.0, v122
	v_add_f32_e32 v160, 1.0, v123
	v_add_f32_e32 v161, 1.0, v124
	v_rcp_f32_e32 v118, v115
	v_rcp_f32_e32 v119, v125
	v_rcp_f32_e32 v120, v126
	v_rcp_f32_e32 v121, v127
	v_rcp_f32_e32 v122, v128
	v_rcp_f32_e32 v123, v129
	v_rcp_f32_e32 v124, v160
	v_rcp_f32_e32 v125, v161
	v_pk_mul_f32 v[110:111], v[110:111], v[118:119]
	v_pk_mul_f32 v[112:113], v[112:113], v[120:121]
	v_pk_mul_f32 v[106:107], v[106:107], v[122:123]
	v_pk_mul_f32 v[108:109], v[108:109], v[124:125]
	v_pk_mul_f32 v[102:103], v[102:103], v[110:111]
	v_pk_mul_f32 v[104:105], v[104:105], v[112:113]
	v_pk_mul_f32 v[106:107], v[98:99], v[106:107]
	v_pk_mul_f32 v[108:109], v[100:101], v[108:109]
	v_cvt_pk_bf16_f32 v98, v102, v103
	v_cvt_pk_bf16_f32 v99, v104, v105
	v_cvt_pk_bf16_f32 v100, v106, v107
	v_cvt_pk_bf16_f32 v101, v108, v109
	global_store_dwordx4 v[116:117], v[98:101], off
	s_nop 1
	v_or_b32_e32 v98, 48, v159
	v_mad_i64_i32 v[100:101], s[28:29], v114, s45, v[148:149]
	v_lshl_add_u64 v[100:101], v[100:101], 0, v[150:151]
	v_pk_mul_f32 v[94:95], v[94:95], v[206:207] op_sel_hi:[1,0]
	v_pk_mul_f32 v[96:97], v[96:97], v[206:207] op_sel_hi:[1,0]
	v_pk_mul_f32 v[90:91], v[90:91], v[206:207] op_sel_hi:[1,0]
	v_pk_mul_f32 v[92:93], v[92:93], v[206:207] op_sel_hi:[1,0]
	v_pk_mul_f32 v[86:87], v[86:87], v[206:207] op_sel_hi:[1,0]
	v_pk_mul_f32 v[88:89], v[88:89], v[206:207] op_sel_hi:[1,0]
	v_pk_mul_f32 v[82:83], v[82:83], v[206:207] op_sel_hi:[1,0]
	v_pk_mul_f32 v[84:85], v[84:85], v[206:207] op_sel_hi:[1,0]
	v_mul_f32_e32 v99, 0xbfb8aa3b, v94
	v_mul_f32_e32 v102, 0xbfb8aa3b, v95
	v_mul_f32_e32 v103, 0xbfb8aa3b, v96
	v_mul_f32_e32 v104, 0xbfb8aa3b, v97
	v_mul_f32_e32 v105, 0xbfb8aa3b, v90
	v_mul_f32_e32 v106, 0xbfb8aa3b, v91
	v_mul_f32_e32 v107, 0xbfb8aa3b, v92
	v_mul_f32_e32 v108, 0xbfb8aa3b, v93
	v_exp_f32_e32 v99, v99
	v_exp_f32_e32 v102, v102
	v_exp_f32_e32 v103, v103
	v_exp_f32_e32 v104, v104
	v_exp_f32_e32 v105, v105
	v_exp_f32_e32 v106, v106
	v_exp_f32_e32 v107, v107
	v_exp_f32_e32 v108, v108
	v_add_f32_e32 v99, 1.0, v99
	v_add_f32_e32 v109, 1.0, v102
	v_add_f32_e32 v110, 1.0, v103
	v_add_f32_e32 v111, 1.0, v104
	v_add_f32_e32 v112, 1.0, v105
	v_add_f32_e32 v113, 1.0, v106
	v_add_f32_e32 v114, 1.0, v107
	v_add_f32_e32 v115, 1.0, v108
	v_rcp_f32_e32 v102, v99
	v_rcp_f32_e32 v103, v109
	v_rcp_f32_e32 v104, v110
	v_rcp_f32_e32 v105, v111
	v_rcp_f32_e32 v106, v112
	v_rcp_f32_e32 v107, v113
	v_rcp_f32_e32 v108, v114
	v_rcp_f32_e32 v109, v115
	v_pk_mul_f32 v[94:95], v[94:95], v[102:103]
	v_pk_mul_f32 v[96:97], v[96:97], v[104:105]
	v_pk_mul_f32 v[90:91], v[90:91], v[106:107]
	v_pk_mul_f32 v[92:93], v[92:93], v[108:109]
	v_pk_mul_f32 v[86:87], v[86:87], v[94:95]
	v_pk_mul_f32 v[88:89], v[88:89], v[96:97]
	v_pk_mul_f32 v[90:91], v[82:83], v[90:91]
	v_pk_mul_f32 v[92:93], v[84:85], v[92:93]
	v_cvt_pk_bf16_f32 v82, v86, v87
	v_cvt_pk_bf16_f32 v83, v88, v89
	v_cvt_pk_bf16_f32 v84, v90, v91
	v_cvt_pk_bf16_f32 v85, v92, v93
	global_store_dwordx4 v[100:101], v[82:85], off
	s_nop 1
	v_add_u32_e32 v82, 0x80, v159
	v_mad_i64_i32 v[84:85], s[28:29], v98, s45, v[148:149]
	v_lshl_add_u64 v[84:85], v[84:85], 0, v[150:151]
	v_pk_mul_f32 v[78:79], v[78:79], v[210:211] op_sel_hi:[1,0]
	v_pk_mul_f32 v[80:81], v[80:81], v[210:211] op_sel_hi:[1,0]
	v_pk_mul_f32 v[74:75], v[74:75], v[210:211] op_sel_hi:[1,0]
	v_pk_mul_f32 v[76:77], v[76:77], v[210:211] op_sel_hi:[1,0]
	v_pk_mul_f32 v[70:71], v[70:71], v[210:211] op_sel_hi:[1,0]
; __device__ __forceinline__ unsigned cvt_pk_bf16(float lo, float hi) { f32x2_cv v = {lo, hi}; bf16x2_cv b = __builtin_convertvector(v, bf16x2_cv); return __builtin_bit_cast(unsigned, b); }
; __device__ __forceinline__ float fast_sigmoid(float x) { return __builtin_amdgcn_rcpf(1.0f + __expf(-x)); }
;     __device__ __forceinline__ void operator()(const f32x4 (&acc)[2][2][4][2], const Unit& u, int wr, int wc, int fr, int fq) const {
;     ...
;                 int row = row0 + ai * HALF + m * 16; asm volatile("" : "+v"(row));
;                 const float rs = SS ? rstd_from_ss(SS + (size_t)row * 16, fq) : 1.0f;
;                 float o[8];
; #pragma unroll
;                 for (int n = 0; n < 2; ++n)
; #pragma unroll
;                     for (int i = 0; i < 4; ++i) { const float g = acc[ai][0][m][n][i] * rs, up = acc[ai][1][m][n][i] * rs; o[4 * n + i] = g * fast_sigmoid(g) * up; }
;                 u32x4 w; w.x = cvt_pk_bf16(o[0], o[1]); w.y = cvt_pk_bf16(o[2], o[3]); w.z = cvt_pk_bf16(o[4], o[5]); w.w = cvt_pk_bf16(o[6], o[7]);
;                 *(u32x4*)(O + (size_t)row * 2816 + col0) = w;
	v_pk_mul_f32 v[72:73], v[72:73], v[210:211] op_sel_hi:[1,0]
	v_pk_mul_f32 v[66:67], v[66:67], v[210:211] op_sel_hi:[1,0]
	v_pk_mul_f32 v[68:69], v[68:69], v[210:211] op_sel_hi:[1,0]
	v_mul_f32_e32 v83, 0xbfb8aa3b, v78
	v_mul_f32_e32 v86, 0xbfb8aa3b, v79
	v_mul_f32_e32 v87, 0xbfb8aa3b, v80
	v_mul_f32_e32 v88, 0xbfb8aa3b, v81
	v_mul_f32_e32 v89, 0xbfb8aa3b, v74
	v_mul_f32_e32 v90, 0xbfb8aa3b, v75
	v_mul_f32_e32 v91, 0xbfb8aa3b, v76
	v_mul_f32_e32 v92, 0xbfb8aa3b, v77
	v_exp_f32_e32 v83, v83
	v_exp_f32_e32 v86, v86
	v_exp_f32_e32 v87, v87
	v_exp_f32_e32 v88, v88
	v_exp_f32_e32 v89, v89
	v_exp_f32_e32 v90, v90
	v_exp_f32_e32 v91, v91
	v_exp_f32_e32 v92, v92
	v_add_f32_e32 v83, 1.0, v83
	v_add_f32_e32 v93, 1.0, v86
	v_add_f32_e32 v94, 1.0, v87
	v_add_f32_e32 v95, 1.0, v88
	v_add_f32_e32 v96, 1.0, v89
	v_add_f32_e32 v97, 1.0, v90
	v_add_f32_e32 v98, 1.0, v91
	v_add_f32_e32 v99, 1.0, v92
	v_rcp_f32_e32 v86, v83
	v_rcp_f32_e32 v87, v93
	v_rcp_f32_e32 v88, v94
	v_rcp_f32_e32 v89, v95
	v_rcp_f32_e32 v90, v96
	v_rcp_f32_e32 v91, v97
	v_rcp_f32_e32 v92, v98
	v_rcp_f32_e32 v93, v99
	v_pk_mul_f32 v[78:79], v[78:79], v[86:87]
	v_pk_mul_f32 v[80:81], v[80:81], v[88:89]
	v_pk_mul_f32 v[74:75], v[74:75], v[90:91]
	v_pk_mul_f32 v[76:77], v[76:77], v[92:93]
	v_pk_mul_f32 v[70:71], v[70:71], v[78:79]
	v_pk_mul_f32 v[72:73], v[72:73], v[80:81]
	v_pk_mul_f32 v[74:75], v[66:67], v[74:75]
	v_pk_mul_f32 v[76:77], v[68:69], v[76:77]
	v_cvt_pk_bf16_f32 v66, v70, v71
	v_cvt_pk_bf16_f32 v67, v72, v73
	v_cvt_pk_bf16_f32 v68, v74, v75
	v_cvt_pk_bf16_f32 v69, v76, v77
	global_store_dwordx4 v[84:85], v[66:69], off
	s_nop 1
	v_add_u32_e32 v66, 0x90, v159
	v_mad_i64_i32 v[68:69], s[28:29], v82, s45, v[148:149]
	v_lshl_add_u64 v[68:69], v[68:69], 0, v[150:151]
	v_pk_mul_f32 v[62:63], v[62:63], v[214:215] op_sel_hi:[1,0]
	v_pk_mul_f32 v[64:65], v[64:65], v[214:215] op_sel_hi:[1,0]
	v_pk_mul_f32 v[58:59], v[58:59], v[214:215] op_sel_hi:[1,0]
	v_pk_mul_f32 v[60:61], v[60:61], v[214:215] op_sel_hi:[1,0]
	v_pk_mul_f32 v[54:55], v[54:55], v[214:215] op_sel_hi:[1,0]
	v_pk_mul_f32 v[56:57], v[56:57], v[214:215] op_sel_hi:[1,0]
	v_pk_mul_f32 v[50:51], v[50:51], v[214:215] op_sel_hi:[1,0]
	v_pk_mul_f32 v[52:53], v[52:53], v[214:215] op_sel_hi:[1,0]
	v_mul_f32_e32 v67, 0xbfb8aa3b, v62
	v_mul_f32_e32 v70, 0xbfb8aa3b, v63
	v_mul_f32_e32 v71, 0xbfb8aa3b, v64
	v_mul_f32_e32 v72, 0xbfb8aa3b, v65
	v_mul_f32_e32 v73, 0xbfb8aa3b, v58
	v_mul_f32_e32 v74, 0xbfb8aa3b, v59
	v_mul_f32_e32 v75, 0xbfb8aa3b, v60
	v_mul_f32_e32 v76, 0xbfb8aa3b, v61
	v_exp_f32_e32 v67, v67
	v_exp_f32_e32 v70, v70
	v_exp_f32_e32 v71, v71
	v_exp_f32_e32 v72, v72
	v_exp_f32_e32 v73, v73
	v_exp_f32_e32 v74, v74
	v_exp_f32_e32 v75, v75
	v_exp_f32_e32 v76, v76
	v_add_f32_e32 v67, 1.0, v67
	v_add_f32_e32 v77, 1.0, v70
	v_add_f32_e32 v78, 1.0, v71
	v_add_f32_e32 v79, 1.0, v72
	v_add_f32_e32 v80, 1.0, v73
	v_add_f32_e32 v81, 1.0, v74
	v_add_f32_e32 v82, 1.0, v75
	v_add_f32_e32 v83, 1.0, v76
	v_rcp_f32_e32 v70, v67
	v_rcp_f32_e32 v71, v77
	v_rcp_f32_e32 v72, v78
	v_rcp_f32_e32 v73, v79
	v_rcp_f32_e32 v74, v80
	v_rcp_f32_e32 v75, v81
	v_rcp_f32_e32 v76, v82
	v_rcp_f32_e32 v77, v83
	v_pk_mul_f32 v[62:63], v[62:63], v[70:71]
	v_pk_mul_f32 v[64:65], v[64:65], v[72:73]
	v_pk_mul_f32 v[58:59], v[58:59], v[74:75]
	v_pk_mul_f32 v[60:61], v[60:61], v[76:77]
	v_pk_mul_f32 v[54:55], v[54:55], v[62:63]
	v_pk_mul_f32 v[56:57], v[56:57], v[64:65]
	v_pk_mul_f32 v[58:59], v[50:51], v[58:59]
	v_pk_mul_f32 v[60:61], v[52:53], v[60:61]
	v_cvt_pk_bf16_f32 v50, v54, v55
	v_cvt_pk_bf16_f32 v51, v56, v57
	v_cvt_pk_bf16_f32 v52, v58, v59
	v_cvt_pk_bf16_f32 v53, v60, v61
	global_store_dwordx4 v[68:69], v[50:53], off
	s_nop 1
	v_add_u32_e32 v50, 0xa0, v159
	v_mad_i64_i32 v[52:53], s[28:29], v66, s45, v[148:149]
	v_lshl_add_u64 v[52:53], v[52:53], 0, v[150:151]
	v_pk_mul_f32 v[46:47], v[46:47], v[218:219] op_sel_hi:[1,0]
	v_pk_mul_f32 v[48:49], v[48:49], v[218:219] op_sel_hi:[1,0]
	v_pk_mul_f32 v[42:43], v[42:43], v[218:219] op_sel_hi:[1,0]
	v_pk_mul_f32 v[44:45], v[44:45], v[218:219] op_sel_hi:[1,0]
	v_pk_mul_f32 v[38:39], v[38:39], v[218:219] op_sel_hi:[1,0]
	v_pk_mul_f32 v[40:41], v[40:41], v[218:219] op_sel_hi:[1,0]
	v_pk_mul_f32 v[34:35], v[34:35], v[218:219] op_sel_hi:[1,0]
	v_pk_mul_f32 v[36:37], v[36:37], v[218:219] op_sel_hi:[1,0]
	v_mul_f32_e32 v51, 0xbfb8aa3b, v46
	v_mul_f32_e32 v54, 0xbfb8aa3b, v47
	v_mul_f32_e32 v55, 0xbfb8aa3b, v48
	v_mul_f32_e32 v56, 0xbfb8aa3b, v49
	v_mul_f32_e32 v57, 0xbfb8aa3b, v42
	v_mul_f32_e32 v58, 0xbfb8aa3b, v43
	v_mul_f32_e32 v59, 0xbfb8aa3b, v44
	v_mul_f32_e32 v60, 0xbfb8aa3b, v45
	v_exp_f32_e32 v51, v51
	v_exp_f32_e32 v54, v54
	v_exp_f32_e32 v55, v55
	v_exp_f32_e32 v56, v56
	v_exp_f32_e32 v57, v57
	v_exp_f32_e32 v58, v58
	v_exp_f32_e32 v59, v59
	v_exp_f32_e32 v60, v60
	v_add_f32_e32 v51, 1.0, v51
	v_add_f32_e32 v61, 1.0, v54
	v_add_f32_e32 v62, 1.0, v55
	v_add_f32_e32 v63, 1.0, v56
	v_add_f32_e32 v64, 1.0, v57
	v_add_f32_e32 v65, 1.0, v58
	v_add_f32_e32 v66, 1.0, v59
; __device__ __forceinline__ unsigned cvt_pk_bf16(float lo, float hi) { f32x2_cv v = {lo, hi}; bf16x2_cv b = __builtin_convertvector(v, bf16x2_cv); return __builtin_bit_cast(unsigned, b); }
; __device__ __forceinline__ float fast_sigmoid(float x) { return __builtin_amdgcn_rcpf(1.0f + __expf(-x)); }
;     __device__ __forceinline__ void operator()(const f32x4 (&acc)[2][2][4][2], const Unit& u, int wr, int wc, int fr, int fq) const {
;     ...
;                 int row = row0 + ai * HALF + m * 16; asm volatile("" : "+v"(row));
;                 const float rs = SS ? rstd_from_ss(SS + (size_t)row * 16, fq) : 1.0f;
;                 float o[8];
; #pragma unroll
;                 for (int n = 0; n < 2; ++n)
; #pragma unroll
;                     for (int i = 0; i < 4; ++i) { const float g = acc[ai][0][m][n][i] * rs, up = acc[ai][1][m][n][i] * rs; o[4 * n + i] = g * fast_sigmoid(g) * up; }
;                 u32x4 w; w.x = cvt_pk_bf16(o[0], o[1]); w.y = cvt_pk_bf16(o[2], o[3]); w.z = cvt_pk_bf16(o[4], o[5]); w.w = cvt_pk_bf16(o[6], o[7]);
;                 *(u32x4*)(O + (size_t)row * 2816 + col0) = w;
	v_add_f32_e32 v67, 1.0, v60
	v_rcp_f32_e32 v54, v51
	v_rcp_f32_e32 v55, v61
	v_rcp_f32_e32 v56, v62
	v_rcp_f32_e32 v57, v63
	v_rcp_f32_e32 v58, v64
	v_rcp_f32_e32 v59, v65
	v_rcp_f32_e32 v60, v66
	v_rcp_f32_e32 v61, v67
	v_pk_mul_f32 v[46:47], v[46:47], v[54:55]
	v_pk_mul_f32 v[48:49], v[48:49], v[56:57]
	v_pk_mul_f32 v[42:43], v[42:43], v[58:59]
	v_pk_mul_f32 v[44:45], v[44:45], v[60:61]
	v_pk_mul_f32 v[38:39], v[38:39], v[46:47]
	v_pk_mul_f32 v[40:41], v[40:41], v[48:49]
	v_pk_mul_f32 v[42:43], v[34:35], v[42:43]
	v_pk_mul_f32 v[44:45], v[36:37], v[44:45]
	v_cvt_pk_bf16_f32 v34, v38, v39
	v_cvt_pk_bf16_f32 v35, v40, v41
	v_cvt_pk_bf16_f32 v36, v42, v43
	v_cvt_pk_bf16_f32 v37, v44, v45
	global_store_dwordx4 v[52:53], v[34:37], off
	s_nop 1
	v_add_u32_e32 v34, 0xb0, v159
	v_mad_i64_i32 v[36:37], s[28:29], v50, s45, v[148:149]
	v_lshl_add_u64 v[36:37], v[36:37], 0, v[150:151]
	v_pk_mul_f32 v[30:31], v[30:31], v[222:223] op_sel_hi:[1,0]
	v_pk_mul_f32 v[32:33], v[32:33], v[222:223] op_sel_hi:[1,0]
	v_pk_mul_f32 v[26:27], v[26:27], v[222:223] op_sel_hi:[1,0]
	v_pk_mul_f32 v[28:29], v[28:29], v[222:223] op_sel_hi:[1,0]
	v_pk_mul_f32 v[22:23], v[22:23], v[222:223] op_sel_hi:[1,0]
	v_pk_mul_f32 v[24:25], v[24:25], v[222:223] op_sel_hi:[1,0]
	v_pk_mul_f32 v[18:19], v[18:19], v[222:223] op_sel_hi:[1,0]
	v_pk_mul_f32 v[20:21], v[20:21], v[222:223] op_sel_hi:[1,0]
	v_mul_f32_e32 v35, 0xbfb8aa3b, v30
	v_mul_f32_e32 v38, 0xbfb8aa3b, v31
	v_mul_f32_e32 v39, 0xbfb8aa3b, v32
	v_mul_f32_e32 v40, 0xbfb8aa3b, v33
	v_mul_f32_e32 v41, 0xbfb8aa3b, v26
	v_mul_f32_e32 v42, 0xbfb8aa3b, v27
	v_mul_f32_e32 v43, 0xbfb8aa3b, v28
	v_mul_f32_e32 v44, 0xbfb8aa3b, v29
	v_exp_f32_e32 v35, v35
	v_exp_f32_e32 v38, v38
	v_exp_f32_e32 v39, v39
	v_exp_f32_e32 v40, v40
	v_exp_f32_e32 v41, v41
	v_exp_f32_e32 v42, v42
	v_exp_f32_e32 v43, v43
	v_exp_f32_e32 v44, v44
	v_add_f32_e32 v35, 1.0, v35
	v_add_f32_e32 v45, 1.0, v38
	v_add_f32_e32 v46, 1.0, v39
	v_add_f32_e32 v47, 1.0, v40
	v_add_f32_e32 v48, 1.0, v41
	v_add_f32_e32 v49, 1.0, v42
	v_add_f32_e32 v50, 1.0, v43
	v_add_f32_e32 v51, 1.0, v44
	v_rcp_f32_e32 v38, v35
	v_rcp_f32_e32 v39, v45
	v_rcp_f32_e32 v40, v46
	v_rcp_f32_e32 v41, v47
	v_rcp_f32_e32 v42, v48
	v_rcp_f32_e32 v43, v49
	v_rcp_f32_e32 v44, v50
	v_rcp_f32_e32 v45, v51
	v_pk_mul_f32 v[30:31], v[30:31], v[38:39]
	v_pk_mul_f32 v[32:33], v[32:33], v[40:41]
	v_pk_mul_f32 v[26:27], v[26:27], v[42:43]
	v_pk_mul_f32 v[28:29], v[28:29], v[44:45]
	v_pk_mul_f32 v[22:23], v[22:23], v[30:31]
	v_pk_mul_f32 v[24:25], v[24:25], v[32:33]
	v_pk_mul_f32 v[26:27], v[18:19], v[26:27]
	v_pk_mul_f32 v[28:29], v[20:21], v[28:29]
	v_cvt_pk_bf16_f32 v18, v22, v23
	v_cvt_pk_bf16_f32 v19, v24, v25
	v_cvt_pk_bf16_f32 v20, v26, v27
	v_cvt_pk_bf16_f32 v21, v28, v29
	global_store_dwordx4 v[36:37], v[18:21], off
	s_nop 1
	s_andn2_b64 vcc, exec, s[10:11]
	v_mad_i64_i32 v[18:19], s[28:29], v34, s45, v[148:149]
	v_lshl_add_u64 v[18:19], v[18:19], 0, v[150:151]
	v_pk_mul_f32 v[14:15], v[14:15], v[226:227] op_sel_hi:[1,0]
	v_pk_mul_f32 v[16:17], v[16:17], v[226:227] op_sel_hi:[1,0]
	v_pk_mul_f32 v[10:11], v[10:11], v[226:227] op_sel_hi:[1,0]
	v_pk_mul_f32 v[12:13], v[12:13], v[226:227] op_sel_hi:[1,0]
	v_pk_mul_f32 v[6:7], v[6:7], v[226:227] op_sel_hi:[1,0]
	v_pk_mul_f32 v[8:9], v[8:9], v[226:227] op_sel_hi:[1,0]
	v_pk_mul_f32 v[2:3], v[2:3], v[226:227] op_sel_hi:[1,0]
	v_pk_mul_f32 v[4:5], v[4:5], v[226:227] op_sel_hi:[1,0]
	v_mul_f32_e32 v20, 0xbfb8aa3b, v14
	v_mul_f32_e32 v21, 0xbfb8aa3b, v15
	v_mul_f32_e32 v22, 0xbfb8aa3b, v16
	v_mul_f32_e32 v23, 0xbfb8aa3b, v17
	v_mul_f32_e32 v24, 0xbfb8aa3b, v10
	v_mul_f32_e32 v25, 0xbfb8aa3b, v11
	v_mul_f32_e32 v26, 0xbfb8aa3b, v12
	v_mul_f32_e32 v27, 0xbfb8aa3b, v13
	v_exp_f32_e32 v20, v20
	v_exp_f32_e32 v21, v21
	v_exp_f32_e32 v22, v22
	v_exp_f32_e32 v23, v23
	v_exp_f32_e32 v24, v24
	v_exp_f32_e32 v25, v25
	v_exp_f32_e32 v26, v26
	v_exp_f32_e32 v27, v27
	v_add_f32_e32 v20, 1.0, v20
	v_add_f32_e32 v21, 1.0, v21
	v_add_f32_e32 v22, 1.0, v22
	v_add_f32_e32 v23, 1.0, v23
	v_add_f32_e32 v24, 1.0, v24
	v_add_f32_e32 v25, 1.0, v25
	v_add_f32_e32 v26, 1.0, v26
	v_add_f32_e32 v27, 1.0, v27
	v_rcp_f32_e32 v20, v20
	v_rcp_f32_e32 v21, v21
	v_rcp_f32_e32 v22, v22
	v_rcp_f32_e32 v23, v23
	v_rcp_f32_e32 v24, v24
	v_rcp_f32_e32 v25, v25
	v_rcp_f32_e32 v26, v26
	v_rcp_f32_e32 v27, v27
	v_pk_mul_f32 v[14:15], v[14:15], v[20:21]
	v_pk_mul_f32 v[16:17], v[16:17], v[22:23]
	v_pk_mul_f32 v[10:11], v[10:11], v[24:25]
	v_pk_mul_f32 v[12:13], v[12:13], v[26:27]
	v_pk_mul_f32 v[6:7], v[6:7], v[14:15]
	v_pk_mul_f32 v[8:9], v[8:9], v[16:17]
	v_pk_mul_f32 v[10:11], v[2:3], v[10:11]
	v_pk_mul_f32 v[12:13], v[4:5], v[12:13]
	v_cvt_pk_bf16_f32 v2, v6, v7
	v_cvt_pk_bf16_f32 v3, v8, v9
	v_cvt_pk_bf16_f32 v4, v10, v11
	v_cvt_pk_bf16_f32 v5, v12, v13
	s_mov_b64 s[10:11], -1
	global_store_dwordx4 v[18:19], v[2:5], off
	s_cbranch_vccnz .LBB0_1072
	s_andn2_b64 vcc, exec, s[4:5]
	s_cbranch_vccnz .LBB0_1071
	s_barrier
	s_branch .LBB0_1071
